# fused P6: the two residual fragments fetched behind the last barrier are read from LDS where first used (counted wait past the 7 row-sum atomics), not at the epilogue start
# speedup vs baseline: 1.0025x; 1.0001x over previous
; __device__ __forceinline__ unsigned lane_id_fresh() { unsigned m = ~0u; asm volatile("" : "+s"(m)); return __builtin_amdgcn_mbcnt_hi(m, __builtin_amdgcn_mbcnt_lo(m, 0u)); }
;     __device__ __forceinline__ void operator()(f32x4 (&acc)[2][2][4][2], const Unit& u, int wr, int wc, int fr, int fq) const {
;         int l_ = (int)lane_id_fresh(); asm volatile("" : "+v"(l_)); fr = l_ & 15; fq = l_ >> 4;
;         const int row0 = u.pm * BM + wr * 64 + fr, col0 = u.pn * BM + wc * 32 + 8 * fq;
;         {
;             u32x4 bv[2][4][2];
; #pragma unroll
;             for (int ai = 0; ai < 2; ++ai)
; #pragma unroll
;                 for (int m = 0; m < 4; ++m) { const size_t off = (size_t)(row0 + ai * HALF + m * 16) * ldc + col0;
; #pragma unroll
;                     for (int bj = 0; bj < 2; ++bj) bv[ai][m][bj] = __builtin_nontemporal_load((const u32x4*)(hb + off + bj * HALF)); }
; #pragma unroll
;             for (int ai = 0; ai < 2; ++ai)
; #pragma unroll
;                 for (int m = 0; m < 4; ++m) { const int r = row0 + ai * HALF + m * 16; float s = 0.f;
; #pragma unroll
;                     for (int bj = 0; bj < 2; ++bj) { const u32x4 b = bv[ai][m][bj];
;                         f32x4 o0 = acc[ai][bj][m][0], o1 = acc[ai][bj][m][1];
;                         o0[0] += __builtin_bit_cast(float, b.x << 16); o0[1] += __builtin_bit_cast(float, b.x & 0xffff0000u);
;                         o0[2] += __builtin_bit_cast(float, b.y << 16); o0[3] += __builtin_bit_cast(float, b.y & 0xffff0000u);
;                         o1[0] += __builtin_bit_cast(float, b.z << 16); o1[1] += __builtin_bit_cast(float, b.z & 0xffff0000u);
;                         o1[2] += __builtin_bit_cast(float, b.w << 16); o1[3] += __builtin_bit_cast(float, b.w & 0xffff0000u);
;                         s += ((o0[0] * o0[0] + o0[1] * o0[1]) + (o0[2] * o0[2] + o0[3] * o0[3])) + ((o1[0] * o1[0] + o1[1] * o1[1]) + (o1[2] * o1[2] + o1[3] * o1[3]));
;                         acc[ai][bj][m][0] = o0; acc[ai][bj][m][1] = o1; }
;                     s += __shfl_xor(s, 16); s += __shfl_xor(s, 32);
;                     if (fq == 0) (void)__hip_atomic_fetch_add(sx + r, (1ull << 40) | (unsigned long long)(s * 16384.0f + 0.5f), __ATOMIC_RELAXED, __HIP_MEMORY_SCOPE_AGENT); }
.LBB0_886:
	s_mov_b32 s20, s70
	s_lshl_b32 s21, s74, 8
	v_mbcnt_lo_u32_b32 v128, s20, 0
	v_mbcnt_hi_u32_b32 v231, s20, v128
	s_lshl_b32 s20, s75, 8
	v_ashrrev_i32_e32 v128, 1, v231
	s_add_i32 s20, s20, s48
	s_or_b32 s21, s21, s50
	v_and_b32_e32 v128, -8, v128
	v_and_or_b32 v210, v231, 15, s20
	v_add_u32_e32 v208, s21, v128
	v_ashrrev_i32_e32 v209, 31, v208
	v_ashrrev_i32_e32 v211, 31, v210
	v_lshl_add_u64 v[136:137], v[208:209], 1, s[30:31]
	v_lshlrev_b64 v[128:129], 12, v[210:211]
	v_lshl_add_u64 v[128:129], v[136:137], 0, v[128:129]
	v_mbcnt_lo_u32_b32 v248, -1, 0
	v_mbcnt_hi_u32_b32 v248, -1, v248
	v_lshl_add_u32 v248, v248, 4, s33
	v_add_u32_e32 v250, 0x10000, v248
	s_waitcnt vmcnt(2)
	ds_read_b128 v[188:191], v250 offset:0
	ds_read_b128 v[184:187], v250 offset:8192
	v_or_b32_e32 v212, 16, v210
	v_ashrrev_i32_e32 v213, 31, v212
	v_lshlrev_b64 v[128:129], 12, v[212:213]
	v_or_b32_e32 v214, 32, v210
	v_lshl_add_u64 v[128:129], v[136:137], 0, v[128:129]
	v_ashrrev_i32_e32 v215, 31, v214
	ds_read_b128 v[180:183], v250 offset:16384
	ds_read_b128 v[176:179], v250 offset:24576
	v_lshlrev_b64 v[128:129], 12, v[214:215]
	v_or_b32_e32 v216, 48, v210
	v_lshl_add_u64 v[128:129], v[136:137], 0, v[128:129]
	v_ashrrev_i32_e32 v217, 31, v216
	ds_read_b128 v[172:175], v248 offset:0
	ds_read_b128 v[168:171], v248 offset:8192
	v_lshlrev_b64 v[128:129], 12, v[216:217]
	v_add_u32_e32 v218, 0x80, v210
	v_lshl_add_u64 v[128:129], v[136:137], 0, v[128:129]
	v_ashrrev_i32_e32 v219, 31, v218
	ds_read_b128 v[164:167], v248 offset:16384
	ds_read_b128 v[160:163], v248 offset:24576
	v_lshlrev_b64 v[128:129], 12, v[218:219]
	v_add_u32_e32 v220, 0x90, v210
	v_lshl_add_u64 v[128:129], v[136:137], 0, v[128:129]
	v_ashrrev_i32_e32 v221, 31, v220
	ds_read_b128 v[156:159], v250 offset:32768
	ds_read_b128 v[152:155], v250 offset:40960
	v_lshlrev_b64 v[128:129], 12, v[220:221]
	v_add_u32_e32 v222, 0xa0, v210
	v_add_u32_e32 v224, 0xb0, v210
	v_lshl_add_u64 v[128:129], v[136:137], 0, v[128:129]
	v_ashrrev_i32_e32 v223, 31, v222
	v_ashrrev_i32_e32 v225, 31, v224
	ds_read_b128 v[148:151], v250 offset:49152
	ds_read_b128 v[140:143], v250 offset:57344
	v_lshlrev_b64 v[128:129], 12, v[222:223]
	v_lshlrev_b64 v[138:139], 12, v[224:225]
	v_lshl_add_u64 v[128:129], v[136:137], 0, v[128:129]
	v_lshl_add_u64 v[136:137], v[136:137], 0, v[138:139]
	ds_read_b128 v[132:135], v248 offset:32768
	s_nop 0
	ds_read_b128 v[128:131], v248 offset:40960
	s_nop 0
	s_nop 0
	v_and_b32_e32 v230, 64, v229
	v_xor_b32_e32 v207, 16, v229
	v_add_u32_e32 v230, 64, v230
	v_cmp_lt_i32_e32 vcc, v207, v230
	v_xor_b32_e32 v232, 32, v229
	s_waitcnt lgkmcnt(0)
	v_and_b32_e32 v233, 0xffff0000, v188
	v_cndmask_b32_e32 v207, v229, v207, vcc
	v_cmp_lt_i32_e32 vcc, v232, v230
	v_lshlrev_b32_e32 v236, 16, v184
	v_and_b32_e32 v237, 0xffff0000, v184
	v_cndmask_b32_e32 v230, v229, v232, vcc
	v_lshlrev_b32_e32 v232, 16, v188
	v_lshlrev_b32_e32 v188, 16, v189
	v_and_b32_e32 v189, 0xffff0000, v189
	v_lshlrev_b32_e32 v184, 16, v185
	v_and_b32_e32 v185, 0xffff0000, v185
	v_pk_add_f32 v[126:127], v[126:127], v[188:189]
	v_lshlrev_b32_e32 v188, 16, v190
	v_and_b32_e32 v189, 0xffff0000, v190
	v_pk_add_f32 v[118:119], v[118:119], v[184:185]
	v_lshlrev_b32_e32 v184, 16, v186
	v_and_b32_e32 v185, 0xffff0000, v186
	v_pk_add_f32 v[120:121], v[120:121], v[188:189]
	v_lshlrev_b32_e32 v188, 16, v191
	v_and_b32_e32 v189, 0xffff0000, v191
	v_pk_add_f32 v[116:117], v[116:117], v[236:237]
	v_pk_add_f32 v[112:113], v[112:113], v[184:185]
	v_lshlrev_b32_e32 v184, 16, v187
	v_and_b32_e32 v185, 0xffff0000, v187
	v_pk_add_f32 v[122:123], v[122:123], v[188:189]
	v_pk_add_f32 v[114:115], v[114:115], v[184:185]
	v_pk_mul_f32 v[184:185], v[116:117], v[116:117]
	v_pk_mul_f32 v[186:187], v[118:119], v[118:119]
	v_pk_add_f32 v[124:125], v[124:125], v[232:233]
	v_pk_mul_f32 v[232:233], v[120:121], v[120:121]
	v_pk_mul_f32 v[234:235], v[122:123], v[122:123]
	v_add_f32_e32 v186, v186, v187
	v_add_f32_e32 v184, v184, v185
	v_pk_mul_f32 v[188:189], v[124:125], v[124:125]
	v_pk_mul_f32 v[190:191], v[126:127], v[126:127]
	v_pk_mul_f32 v[236:237], v[112:113], v[112:113]
	v_pk_mul_f32 v[238:239], v[114:115], v[114:115]
	v_add_f32_e32 v184, v184, v186
	v_add_f32_e32 v185, v234, v235
	v_add_f32_e32 v186, v232, v233
	v_cmp_gt_u32_e32 vcc, 16, v231
	v_add_f32_e32 v231, v238, v239
	v_add_f32_e32 v236, v236, v237
	v_add_f32_e32 v185, v186, v185
	v_add_f32_e32 v186, v190, v191
	v_add_f32_e32 v187, v188, v189
	v_add_f32_e32 v231, v236, v231
	v_add_f32_e32 v186, v187, v186
	v_add_f32_e32 v184, v184, v231
	v_add_f32_e32 v185, v186, v185
	v_lshlrev_b32_e32 v207, 2, v207
	v_add_f32_e32 v184, v185, v184
	ds_bpermute_b32 v185, v207, v184
	v_lshlrev_b32_e32 v230, 2, v230
	s_waitcnt lgkmcnt(0)
	v_add_f32_e32 v186, v184, v185
	ds_bpermute_b32 v187, v230, v186
	v_lshl_add_u64 v[184:185], v[210:211], 3, s[46:47]
	s_and_saveexec_b64 s[22:23], vcc
	s_cbranch_execz .LBB0_888
	s_waitcnt lgkmcnt(0)
	v_add_f32_e32 v186, v186, v187
	v_fma_f32 v186, v186, s72, 0.5
	v_trunc_f32_e32 v186, v186
	v_mul_f32_e32 v187, 0x2f800000, v186
	v_floor_f32_e32 v187, v187
	v_fmac_f32_e32 v186, 0xcf800000, v187
	v_cvt_u32_f32_e32 v187, v187
	v_cvt_u32_f32_e32 v186, v186
	v_or_b32_e32 v187, 0x100, v187
	global_atomic_add_x2 v[184:185], v[186:187], off

;     __device__ __forceinline__ const char* b(const Unit& u) const { return (const char*)Bt + (size_t)u.pn * 2 * hB() + (size_t)(u.pm >> gshift) * goff; }
;     __device__ __forceinline__ const char* b(const Unit& u) const { return (const char*)Bt + (size_t)((u.pn >> 4) * 4096 + (u.pn & 15) * 16) * 1024 * 2 + (size_t)(u.pm >> 1) * 512; }
;     __device__ __forceinline__ const char* b(const Unit& u) const { return (const char*)Bt + ((size_t)(((u.pm >> 4) * 1024 + u.pn * 256) * 16 + (u.pm & 15)) * 512) * 2; }
;     __device__ __forceinline__ void operator()(f32x4 (&acc)[2][2][4][2], const Unit& u, int wr, int wc, int fr, int fq) const {
;     ...
;                 for (int m = 0; m < 4; ++m) { const int r = row0 + ai * HALF + m * 16; float s = 0.f;
; #pragma unroll
;                     for (int bj = 0; bj < 2; ++bj) { const u32x4 b = bv[ai][m][bj];
;                         f32x4 o0 = acc[ai][bj][m][0], o1 = acc[ai][bj][m][1];
;                         o0[0] += __builtin_bit_cast(float, b.x << 16); o0[1] += __builtin_bit_cast(float, b.x & 0xffff0000u);
;                         o0[2] += __builtin_bit_cast(float, b.y << 16); o0[3] += __builtin_bit_cast(float, b.y & 0xffff0000u);
;                         o1[0] += __builtin_bit_cast(float, b.z << 16); o1[1] += __builtin_bit_cast(float, b.z & 0xffff0000u);
;                         o1[2] += __builtin_bit_cast(float, b.w << 16); o1[3] += __builtin_bit_cast(float, b.w & 0xffff0000u);
;                         s += ((o0[0] * o0[0] + o0[1] * o0[1]) + (o0[2] * o0[2] + o0[3] * o0[3])) + ((o1[0] * o1[0] + o1[1] * o1[1]) + (o1[2] * o1[2] + o1[3] * o1[3]));
;                         acc[ai][bj][m][0] = o0; acc[ai][bj][m][1] = o1; }
;                     s += __shfl_xor(s, 16); s += __shfl_xor(s, 32);
;                     if (fq == 0) (void)__hip_atomic_fetch_add(sx + r, (1ull << 40) | (unsigned long long)(s * 16384.0f + 0.5f), __ATOMIC_RELAXED, __HIP_MEMORY_SCOPE_AGENT); }
.LBB0_900:
	s_or_b64 exec, exec, s[22:23]
	s_waitcnt vmcnt(7)
	ds_read_b128 v[144:147], v248 offset:49152
	ds_read_b128 v[136:139], v248 offset:57344
	s_waitcnt lgkmcnt(0)
	v_lshlrev_b32_e32 v128, 16, v144
	s_waitcnt lgkmcnt(0)
	v_and_b32_e32 v129, 0xffff0000, v144
	v_lshlrev_b32_e32 v140, 16, v136
	v_and_b32_e32 v141, 0xffff0000, v136
	v_pk_add_f32 v[128:129], v[12:13], v[128:129]
	v_lshlrev_b32_e32 v12, 16, v145
	v_and_b32_e32 v13, 0xffff0000, v145
	v_pk_add_f32 v[140:141], v[4:5], v[140:141]
	v_lshlrev_b32_e32 v4, 16, v137
	v_and_b32_e32 v5, 0xffff0000, v137
	v_pk_add_f32 v[132:133], v[14:15], v[12:13]
	v_lshlrev_b32_e32 v12, 16, v146
	v_and_b32_e32 v13, 0xffff0000, v146
	v_pk_add_f32 v[142:143], v[6:7], v[4:5]
	v_lshlrev_b32_e32 v4, 16, v138
	v_and_b32_e32 v5, 0xffff0000, v138
	v_pk_add_f32 v[130:131], v[8:9], v[12:13]
	v_lshlrev_b32_e32 v8, 16, v147
	v_and_b32_e32 v9, 0xffff0000, v147
	v_pk_add_f32 v[136:137], v[0:1], v[4:5]
	v_lshlrev_b32_e32 v0, 16, v139
	v_and_b32_e32 v1, 0xffff0000, v139
	v_pk_add_f32 v[134:135], v[10:11], v[8:9]
	v_pk_add_f32 v[138:139], v[2:3], v[0:1]
	v_pk_mul_f32 v[0:1], v[140:141], v[140:141]
	v_pk_mul_f32 v[2:3], v[142:143], v[142:143]
	v_pk_mul_f32 v[12:13], v[130:131], v[130:131]
	v_pk_mul_f32 v[14:15], v[134:135], v[134:135]
	v_add_f32_e32 v2, v2, v3
	v_add_f32_e32 v0, v0, v1
	v_pk_mul_f32 v[8:9], v[128:129], v[128:129]
	v_pk_mul_f32 v[10:11], v[132:133], v[132:133]
	v_pk_mul_f32 v[4:5], v[136:137], v[136:137]
	v_pk_mul_f32 v[6:7], v[138:139], v[138:139]
	v_add_f32_e32 v0, v0, v2
	v_add_f32_e32 v1, v14, v15
	v_add_f32_e32 v2, v12, v13
	v_add_f32_e32 v6, v6, v7
	v_add_f32_e32 v4, v4, v5
	v_add_f32_e32 v1, v2, v1
	v_add_f32_e32 v2, v10, v11
	v_add_f32_e32 v3, v8, v9
	v_add_f32_e32 v4, v4, v6
	v_add_f32_e32 v2, v3, v2
	v_add_f32_e32 v0, v0, v4
	v_add_f32_e32 v1, v2, v1
	v_add_f32_e32 v0, v1, v0
	ds_bpermute_b32 v1, v207, v0
	s_waitcnt lgkmcnt(0)
	v_add_f32_e32 v0, v0, v1
	ds_bpermute_b32 v1, v230, v0
	s_and_saveexec_b64 s[22:23], vcc
	s_cbranch_execz .LBB0_902
	s_waitcnt lgkmcnt(0)
	v_add_f32_e32 v0, v0, v1
	v_fma_f32 v0, v0, s72, 0.5
	v_trunc_f32_e32 v0, v0
	v_mul_f32_e32 v1, 0x2f800000, v0
	v_floor_f32_e32 v1, v1
	v_fmac_f32_e32 v0, 0xcf800000, v1
	v_cvt_u32_f32_e32 v1, v1
	v_cvt_u32_f32_e32 v0, v0
	v_or_b32_e32 v1, 0x100, v1
	global_atomic_add_x2 v[184:185], v[0:1], off offset:1408
